# P7 stage-2 Hs-write ladder: 32 serialized ds_read_b32 scale reads replaced by 8 ds_read_b128 issued before the last MFMA, one wait, fresh temps
# baseline (speedup 1.0000x reference)
; #define LAS __attribute__((address_space(3)))
; __device__ __forceinline__ int crow(int r, int hi) { return (r & 3) + 8 * (r >> 2) + 4 * hi; }
; #define MFMA32(a, b, c) __builtin_amdgcn_mfma_f32_32x32x16_bf16((a), (b), (c), 0, 0, 0)
; __device__ __forceinline__ void ml_out_phase(const Args& a, LAS unsigned char* lds) {
;     ...
; #pragma unroll
;     for (int ks = 0; ks < 8; ++ks) { const bf16x8 A = *(const LAS bf16x8*)(Qs + (32 * jb + l32) * 136 + 16 * ks + 8 * hi); const bf16x8 B = *(const LAS bf16x8*)(Cs + (32 * vb + l32) * 136 + 16 * ks + 8 * hi);
;         a2 = MFMA32(A, B, a2); }
; #pragma unroll
;     for (int r = 0; r < 16; ++r) { const int jr = crow(r, hi); Hs[(32 * jb + jr) * 132 + 32 * vb + l32] = a1[r] * wsf[jr] + a2[r] * wsf[32 + jr]; }
;     asm volatile("s_waitcnt lgkmcnt(0)" ::: "memory"); __builtin_amdgcn_s_barrier(); asm volatile("" ::: "memory");
.LBB0_637:
	s_or_b64 exec, exec, s[4:5]
	ds_read_b128 v[2:5], v147
	v_lshlrev_b32_e32 v6, 7, v91
	v_lshlrev_b32_e32 v7, 1, v92
	v_add3_u32 v148, v93, v6, v7
	ds_read_b128 v[6:9], v148 offset:53248
	ds_read_b128 v[90:93], v147 offset:32
	ds_read_b128 v[94:97], v148 offset:53280
	v_lshl_add_u32 v75, v74, 2, v75
	v_or_b32_e32 v74, v74, v119
	s_andn2_b64 vcc, exec, s[96:97]
	s_mov_b64 s[4:5], -1
	s_waitcnt lgkmcnt(2)
	v_mfma_f32_32x32x16_bf16 v[2:17], v[2:5], v[6:9], 0
	s_waitcnt lgkmcnt(0)
	v_mfma_f32_32x32x16_bf16 v[2:17], v[90:93], v[94:97], v[2:17]
	ds_read_b128 v[90:93], v147 offset:64
	ds_read_b128 v[94:97], v148 offset:53312
	ds_read_b128 v[98:101], v147 offset:96
	ds_read_b128 v[102:105], v148 offset:53344
	s_waitcnt lgkmcnt(2)
	v_mfma_f32_32x32x16_bf16 v[2:17], v[90:93], v[94:97], v[2:17]
	s_waitcnt lgkmcnt(0)
	v_mfma_f32_32x32x16_bf16 v[2:17], v[98:101], v[102:105], v[2:17]
	ds_read_b128 v[90:93], v147 offset:128
	ds_read_b128 v[94:97], v148 offset:53376
	ds_read_b128 v[98:101], v147 offset:160
	ds_read_b128 v[102:105], v148 offset:53408
	s_waitcnt lgkmcnt(2)
	v_mfma_f32_32x32x16_bf16 v[2:17], v[90:93], v[94:97], v[2:17]
	s_waitcnt lgkmcnt(0)
	v_mfma_f32_32x32x16_bf16 v[2:17], v[98:101], v[102:105], v[2:17]
	ds_read_b128 v[90:93], v147 offset:192
	ds_read_b128 v[94:97], v148 offset:53440
	ds_read_b128 v[98:101], v147 offset:224
	ds_read_b128 v[102:105], v148 offset:53472
	s_waitcnt lgkmcnt(2)
	v_mfma_f32_32x32x16_bf16 v[2:17], v[90:93], v[94:97], v[2:17]
	ds_read_b128 v[206:209], v75
	ds_read_b128 v[210:213], v75 offset:32
	ds_read_b128 v[214:217], v75 offset:64
	ds_read_b128 v[218:221], v75 offset:96
	ds_read_b128 v[222:225], v75 offset:128
	ds_read_b128 v[226:229], v75 offset:160
	ds_read_b128 v[230:233], v75 offset:192
	ds_read_b128 v[234:237], v75 offset:224
	v_and_b32_e32 v90, 0xffffff80, v120
	v_lshlrev_b32_e32 v93, 2, v146
	v_add3_u32 v90, s78, v90, v93
	v_mad_u32_u24 v93, v74, s79, v90
	v_or_b32_e32 v74, 1, v74
	v_mad_u32_u24 v74, v74, s79, v90
	s_waitcnt lgkmcnt(8)
	v_mfma_f32_32x32x16_bf16 v[2:17], v[98:101], v[102:105], v[2:17]
	v_or_b32_e32 v242, v77, v119
	v_mad_u32_u24 v242, v242, s79, v90
	v_or_b32_e32 v243, v76, v119
	v_mad_u32_u24 v243, v243, s79, v90
	v_or_b32_e32 v244, v78, v119
	v_mad_u32_u24 v244, v244, s79, v90
	v_or_b32_e32 v245, v81, v119
	v_mad_u32_u24 v245, v245, s79, v90
	v_or_b32_e32 v246, v80, v119
	v_mad_u32_u24 v246, v246, s79, v90
	v_or_b32_e32 v247, v79, v119
	v_mad_u32_u24 v247, v247, s79, v90
	v_or_b32_e32 v248, v82, v119
	v_mad_u32_u24 v248, v248, s79, v90
	v_or_b32_e32 v249, v85, v119
	v_mad_u32_u24 v249, v249, s79, v90
	v_or_b32_e32 v250, v84, v119
	v_mad_u32_u24 v250, v250, s79, v90
	v_or_b32_e32 v251, v83, v119
	v_mad_u32_u24 v251, v251, s79, v90
	v_or_b32_e32 v252, v86, v119
	v_mad_u32_u24 v252, v252, s79, v90
	v_or_b32_e32 v253, v89, v119
	v_mad_u32_u24 v253, v253, s79, v90
	v_or_b32_e32 v254, v88, v119
	v_mad_u32_u24 v254, v254, s79, v90
	v_or_b32_e32 v255, v87, v119
	v_mad_u32_u24 v255, v255, s79, v90
	s_waitcnt lgkmcnt(0)
	s_nop 4
	v_mul_f32_e32 v239, v2, v222
	v_fmac_f32_e32 v239, v18, v206
	ds_write_b32 v93, v239
	v_mul_f32_e32 v240, v3, v223
	v_fmac_f32_e32 v240, v19, v207
	ds_write_b32 v74, v240
	v_mul_f32_e32 v241, v4, v224
	v_fmac_f32_e32 v241, v20, v208
	ds_write_b32 v242, v241
	v_mul_f32_e32 v239, v5, v225
	v_fmac_f32_e32 v239, v21, v209
	ds_write_b32 v243, v239
	v_mul_f32_e32 v240, v6, v226
	v_fmac_f32_e32 v240, v22, v210
	ds_write_b32 v244, v240
	v_mul_f32_e32 v241, v7, v227
	v_fmac_f32_e32 v241, v23, v211
	ds_write_b32 v245, v241
	v_mul_f32_e32 v239, v8, v228
	v_fmac_f32_e32 v239, v24, v212
	ds_write_b32 v246, v239
	v_mul_f32_e32 v240, v9, v229
	v_fmac_f32_e32 v240, v25, v213
	ds_write_b32 v247, v240
	v_mul_f32_e32 v241, v10, v230
	v_fmac_f32_e32 v241, v26, v214
	ds_write_b32 v248, v241
	v_mul_f32_e32 v239, v11, v231
	v_fmac_f32_e32 v239, v27, v215
	ds_write_b32 v249, v239
	v_mul_f32_e32 v240, v12, v232
	v_fmac_f32_e32 v240, v28, v216
	ds_write_b32 v250, v240
	v_mul_f32_e32 v241, v13, v233
	v_fmac_f32_e32 v241, v29, v217
	ds_write_b32 v251, v241
	v_mul_f32_e32 v239, v14, v234
	v_fmac_f32_e32 v239, v30, v218
	ds_write_b32 v252, v239
	v_mul_f32_e32 v240, v15, v235
	v_fmac_f32_e32 v240, v31, v219
	ds_write_b32 v253, v240
	v_mul_f32_e32 v241, v16, v236
	v_fmac_f32_e32 v241, v32, v220
	ds_write_b32 v254, v241
	v_mul_f32_e32 v239, v17, v237
	v_fmac_f32_e32 v239, v33, v221
	ds_write_b32 v255, v239
	s_waitcnt lgkmcnt(0)
	s_barrier
	v_cndmask_b32_e64 v2, 0, 1, s[96:97]
	v_cmp_ne_u32_e64 s[0:1], 1, v2
	s_cbranch_vccnz .LBB0_639
	s_add_i32 s3, s72, s93
	s_mov_b64 s[4:5], 0
